# attention: lane^32 max exchange via v_permlane32_swap (no LDS round trip); latent tile loop issues LDS fragment reads first and all staging ds_writes before the row-sum chain
# speedup vs baseline: 1.0057x; 1.0057x over previous
.LBB0_373:
	s_bitcmp1_b32 s17, 0
	s_cselect_b32 s2, 0x2e00, 0
	s_add_i32 s2, s18, s2
	v_add3_u32 v0, s2, v153, v154
	ds_read_b128 v[132:135], v0
	ds_read_b128 v[136:139], v0 offset:32
	ds_read_b128 v[140:143], v0 offset:64
	ds_read_b128 v[160:163], v0 offset:96
	ds_read_b128 v[164:167], v0 offset:128
	ds_read_b128 v[168:171], v0 offset:160
	v_add3_u32 v0, s2, v102, v155
	v_add_u32_e32 v2, 0x1800, v0
	v_add_u32_e32 v0, 0x2000, v0
	ds_read2_b64 v[172:175], v2 offset0:64 offset1:66
	ds_read2_b64 v[176:179], v2 offset0:68 offset1:70
	ds_read2_b64 v[180:183], v0 offset0:128 offset1:130
	ds_read2_b64 v[184:187], v0 offset0:132 offset1:134
	s_add_i32 s2, s19, s17
	s_cmp_lt_i32 s2, 63
	s_cselect_b32 s2, s13, s45
	s_add_i32 s2, s16, s2
	v_add_u32_e32 v0, s2, v145
	v_mad_i64_i32 v[2:3], s[14:15], v0, s48, v[64:65]
	global_load_dwordx4 v[98:101], v[2:3], off
	s_and_saveexec_b64 s[14:15], s[0:1]
	s_cbranch_execz .LBB0_375
	v_add_u32_e32 v0, s2, v146
	v_mad_i64_i32 v[2:3], s[34:35], v0, s48, v[128:129]
	global_load_dwordx4 v[66:69], v[2:3], off
.LBB0_375:
	s_or_b64 exec, exec, s[14:15]
	s_add_i32 s14, s17, 1
	s_ashr_i32 s3, s2, 31
	v_lshl_add_u64 v[2:3], s[2:3], 1, v[130:131]
	global_load_dwordx4 v[94:97], v[2:3], off
	s_bitcmp1_b32 s14, 0
	s_cselect_b32 s2, 0x2e00, 0
	s_waitcnt lgkmcnt(9)
	v_mfma_f32_32x32x16_bf16 v[48:63], v[132:135], v[70:73], 0
	s_add_i32 s15, s18, s2
	s_waitcnt lgkmcnt(8)
	v_mfma_f32_32x32x16_bf16 v[48:63], v[136:139], v[74:77], v[48:63]
	s_waitcnt lgkmcnt(7)
	v_mfma_f32_32x32x16_bf16 v[48:63], v[140:143], v[78:81], v[48:63]
	s_waitcnt lgkmcnt(6)
	v_mfma_f32_32x32x16_bf16 v[48:63], v[160:163], v[82:85], v[48:63]
	s_waitcnt lgkmcnt(5)
	v_mfma_f32_32x32x16_bf16 v[48:63], v[164:167], v[86:89], v[48:63]
	s_waitcnt lgkmcnt(4)
	v_mfma_f32_32x32x16_bf16 v[48:63], v[168:171], v[90:93], v[48:63]
	s_nop 11
	v_max_f32_e32 v0, v49, v49
	v_max_f32_e32 v2, v48, v48
	v_max_f32_e32 v0, v2, v0
	v_max3_f32 v0, v0, v50, v51
	v_max3_f32 v0, v0, v52, v53
	v_max3_f32 v0, v0, v54, v55
	v_max3_f32 v0, v0, v56, v57
	v_max3_f32 v0, v0, v58, v59
	v_max3_f32 v0, v0, v60, v61
	v_max3_f32 v0, v0, v62, v63
	v_mov_b32_e32 v2, v0
	s_nop 1
	v_permlane32_swap_b32_e32 v2, v0
	s_nop 1
	v_max3_f32 v115, v117, v0, v2
	v_sub_f32_e32 v0, v117, v115
	v_sub_f32_e32 v2, v48, v115
	v_sub_f32_e32 v3, v49, v115
	v_sub_f32_e32 v4, v50, v115
	v_sub_f32_e32 v5, v51, v115
	v_sub_f32_e32 v6, v52, v115
	v_sub_f32_e32 v7, v53, v115
	v_sub_f32_e32 v8, v54, v115
	v_sub_f32_e32 v9, v55, v115
	v_exp_f32_e32 v2, v2
	v_exp_f32_e32 v3, v3
	v_exp_f32_e32 v4, v4
	v_exp_f32_e32 v5, v5
	v_exp_f32_e32 v6, v6
	v_exp_f32_e32 v7, v7
	v_exp_f32_e32 v8, v8
	v_exp_f32_e32 v9, v9
	v_exp_f32_e32 v0, v0
	v_cvt_pk_bf16_f32 v48, v2, v3
	v_cvt_pk_bf16_f32 v49, v4, v5
	v_cvt_pk_bf16_f32 v50, v6, v7
	v_pk_mul_f32 v[46:47], v[46:47], v[0:1] op_sel_hi:[1,0]
	v_pk_mul_f32 v[44:45], v[44:45], v[0:1] op_sel_hi:[1,0]
	v_pk_mul_f32 v[42:43], v[42:43], v[0:1] op_sel_hi:[1,0]
	v_pk_mul_f32 v[40:41], v[40:41], v[0:1] op_sel_hi:[1,0]
	v_pk_mul_f32 v[38:39], v[38:39], v[0:1] op_sel_hi:[1,0]
	v_pk_mul_f32 v[36:37], v[36:37], v[0:1] op_sel_hi:[1,0]
	v_pk_mul_f32 v[34:35], v[34:35], v[0:1] op_sel_hi:[1,0]
	v_pk_mul_f32 v[32:33], v[32:33], v[0:1] op_sel_hi:[1,0]
	v_pk_mul_f32 v[30:31], v[30:31], v[0:1] op_sel_hi:[1,0]
	v_cvt_pk_bf16_f32 v51, v8, v9
	v_pk_mul_f32 v[28:29], v[28:29], v[0:1] op_sel_hi:[1,0]
	v_pk_mul_f32 v[26:27], v[26:27], v[0:1] op_sel_hi:[1,0]
	v_pk_mul_f32 v[24:25], v[24:25], v[0:1] op_sel_hi:[1,0]
	v_pk_mul_f32 v[22:23], v[22:23], v[0:1] op_sel_hi:[1,0]
	v_pk_mul_f32 v[20:21], v[20:21], v[0:1] op_sel_hi:[1,0]
	v_pk_mul_f32 v[18:19], v[18:19], v[0:1] op_sel_hi:[1,0]
	v_pk_mul_f32 v[16:17], v[16:17], v[0:1] op_sel_hi:[1,0]
	s_waitcnt lgkmcnt(0)
	v_mfma_f32_32x32x16_bf16 v[32:47], v[172:175], v[48:51], v[32:47]
	v_sub_f32_e32 v10, v56, v115
	v_sub_f32_e32 v11, v57, v115
	v_sub_f32_e32 v12, v58, v115
	v_sub_f32_e32 v13, v59, v115
	v_sub_f32_e32 v14, v60, v115
	v_sub_f32_e32 v15, v61, v115
	v_sub_f32_e32 v52, v62, v115
	v_mfma_f32_32x32x16_bf16 v[16:31], v[180:183], v[48:51], v[16:31]
	v_sub_f32_e32 v49, v63, v115
	v_exp_f32_e32 v10, v10
	v_exp_f32_e32 v11, v11
	v_exp_f32_e32 v12, v12
	v_exp_f32_e32 v13, v13
	v_exp_f32_e32 v14, v14
	v_exp_f32_e32 v15, v15
	v_exp_f32_e32 v48, v52
	v_exp_f32_e32 v49, v49
	v_cvt_pk_bf16_f32 v50, v10, v11
	v_cvt_pk_bf16_f32 v51, v12, v13
	v_cvt_pk_bf16_f32 v52, v14, v15
	v_cvt_pk_bf16_f32 v53, v48, v49
	s_nop 1
	v_mfma_f32_32x32x16_bf16 v[32:47], v[176:179], v[50:53], v[32:47]
	v_mfma_f32_32x32x16_bf16 v[16:31], v[184:187], v[50:53], v[16:31]
	v_add3_u32 v50, s15, v148, v149
	s_waitcnt vmcnt(0)
	ds_write_b128 v50, v[98:101]
	s_and_saveexec_b64 s[2:3], s[0:1]
	v_add3_u32 v50, s15, v150, v156
	ds_write_b128 v50, v[66:69]
	s_or_b64 exec, exec, s[2:3]
	v_add3_u32 v50, s15, v151, v152
	ds_write_b128 v50, v[94:97] offset:6656
	v_add_f32_e32 v2, 0, v2
	v_add_f32_e32 v2, v3, v2
	v_add_f32_e32 v2, v4, v2
	v_add_f32_e32 v2, v5, v2
	v_add_f32_e32 v2, v6, v2
	v_add_f32_e32 v2, v7, v2
	v_add_f32_e32 v2, v8, v2
	v_add_f32_e32 v2, v9, v2
	v_add_f32_e32 v2, v10, v2
	v_add_f32_e32 v2, v11, v2
	v_add_f32_e32 v2, v12, v2
	v_add_f32_e32 v2, v13, v2
	v_add_f32_e32 v2, v14, v2
	v_add_f32_e32 v2, v15, v2
	v_add_f32_e32 v2, v48, v2
	v_add_f32_e32 v98, v49, v2
	s_add_i32 s16, s16, 32
	v_fmac_f32_e32 v98, v113, v0
	s_cmp_eq_u32 s14, 39
	s_waitcnt lgkmcnt(0)
	s_barrier
	s_cbranch_scc1 .LBB0_379
	v_mov_b32_e32 v113, v98
	v_mov_b32_e32 v117, v115
	s_mov_b32 s17, s14
	s_branch .LBB0_373
.LBB0_379:
	v_add3_u32 v0, s15, v153, v154
	ds_read_b128 v[94:97], v0
	ds_read_b128 v[128:131], v0 offset:32
	ds_read_b128 v[132:135], v0 offset:64
	ds_read_b128 v[136:139], v0 offset:96
	ds_read_b128 v[140:143], v0 offset:128
	ds_read_b128 v[160:163], v0 offset:160
	v_add3_u32 v0, s15, v102, v155
	v_add_u32_e32 v2, 0x1800, v0
	v_add_u32_e32 v0, 0x2000, v0
	v_mov_b32_e32 v14, v1
	v_mov_b32_e32 v15, v1
	ds_read2_b64 v[164:167], v2 offset0:64 offset1:66
	ds_read2_b64 v[64:67], v2 offset0:68 offset1:70
	ds_read2_b64 v[168:171], v0 offset0:128 offset1:130
	ds_read2_b64 v[172:175], v0 offset0:132 offset1:134
	v_mov_b32_e32 v0, v1
	v_mov_b32_e32 v2, v1
	v_mov_b32_e32 v3, v1
	v_mov_b32_e32 v4, v1
	v_mov_b32_e32 v5, v1
	v_mov_b32_e32 v6, v1
	v_mov_b32_e32 v7, v1
	v_mov_b32_e32 v8, v1
	v_mov_b32_e32 v9, v1
	v_mov_b32_e32 v10, v1
	v_mov_b32_e32 v11, v1
	v_mov_b32_e32 v12, v1
	v_mov_b32_e32 v13, v1
	v_mov_b64_e32 v[62:63], v[14:15]
	v_mov_b64_e32 v[60:61], v[12:13]
	v_mov_b64_e32 v[58:59], v[10:11]
	v_mov_b64_e32 v[56:57], v[8:9]
	v_mov_b64_e32 v[54:55], v[6:7]
	v_mov_b64_e32 v[52:53], v[4:5]
	v_mov_b64_e32 v[50:51], v[2:3]
	v_mov_b64_e32 v[48:49], v[0:1]
	s_andn2_b64 vcc, exec, s[8:9]
	s_waitcnt lgkmcnt(0)
	v_mfma_f32_32x32x16_bf16 v[48:63], v[94:97], v[70:73], v[48:63]
	s_barrier
	v_mfma_f32_32x32x16_bf16 v[48:63], v[128:131], v[74:77], v[48:63]
	v_mfma_f32_32x32x16_bf16 v[48:63], v[132:135], v[78:81], v[48:63]
	v_mfma_f32_32x32x16_bf16 v[48:63], v[136:139], v[82:85], v[48:63]
	v_mfma_f32_32x32x16_bf16 v[48:63], v[140:143], v[86:89], v[48:63]
	v_mfma_f32_32x32x16_bf16 v[48:63], v[160:163], v[90:93], v[48:63]
	s_nop 11
	v_max_f32_e32 v0, v49, v49
	v_max_f32_e32 v2, v48, v48
	v_max_f32_e32 v0, v2, v0
	v_max3_f32 v0, v0, v50, v51
	v_max3_f32 v0, v0, v52, v53
	v_max3_f32 v0, v0, v54, v55
	v_max3_f32 v0, v0, v56, v57
	v_max3_f32 v0, v0, v58, v59
	v_max3_f32 v0, v0, v60, v61
	v_max3_f32 v0, v0, v62, v63
	v_mov_b32_e32 v2, v0
	s_nop 1
	v_permlane32_swap_b32_e32 v2, v0
	s_nop 1
	v_max3_f32 v0, v115, v0, v2
	v_sub_f32_e32 v3, v48, v0
	v_sub_f32_e32 v4, v49, v0
	v_exp_f32_e32 v3, v3
	v_sub_f32_e32 v5, v50, v0
	v_exp_f32_e32 v4, v4
	v_sub_f32_e32 v6, v51, v0
	v_exp_f32_e32 v5, v5
	v_sub_f32_e32 v2, v115, v0
	v_sub_f32_e32 v7, v52, v0
	v_sub_f32_e32 v10, v55, v0
	v_exp_f32_e32 v6, v6
	v_sub_f32_e32 v8, v53, v0
	v_exp_f32_e32 v7, v7
	v_exp_f32_e32 v49, v10
	v_exp_f32_e32 v10, v2
	v_add_f32_e32 v2, 0, v3
	v_sub_f32_e32 v9, v54, v0
	v_exp_f32_e32 v8, v8
	v_add_f32_e32 v2, v4, v2
	v_exp_f32_e32 v9, v9
	v_add_f32_e32 v2, v5, v2
	v_sub_f32_e32 v11, v56, v0
	v_add_f32_e32 v2, v6, v2
	v_sub_f32_e32 v12, v57, v0
	v_exp_f32_e32 v11, v11
	v_add_f32_e32 v2, v7, v2
	v_exp_f32_e32 v12, v12
	v_add_f32_e32 v2, v8, v2
	v_add_f32_e32 v2, v9, v2
	v_add_f32_e32 v2, v49, v2
	v_add_f32_e32 v2, v11, v2
	v_add_f32_e32 v50, v12, v2
	v_pk_mul_f32 v[46:47], v[46:47], v[10:11] op_sel_hi:[1,0]
	v_pk_mul_f32 v[44:45], v[44:45], v[10:11] op_sel_hi:[1,0]
	v_pk_mul_f32 v[42:43], v[42:43], v[10:11] op_sel_hi:[1,0]
	v_pk_mul_f32 v[40:41], v[40:41], v[10:11] op_sel_hi:[1,0]
	v_pk_mul_f32 v[38:39], v[38:39], v[10:11] op_sel_hi:[1,0]
	v_pk_mul_f32 v[36:37], v[36:37], v[10:11] op_sel_hi:[1,0]
	v_pk_mul_f32 v[34:35], v[34:35], v[10:11] op_sel_hi:[1,0]
	v_pk_mul_f32 v[32:33], v[32:33], v[10:11] op_sel_hi:[1,0]
	v_pk_mul_f32 v[30:31], v[30:31], v[10:11] op_sel_hi:[1,0]
	v_cvt_pk_bf16_f32 v2, v3, v4
	v_cvt_pk_bf16_f32 v3, v5, v6
	v_cvt_pk_bf16_f32 v4, v7, v8
	v_cvt_pk_bf16_f32 v5, v9, v49
	v_pk_mul_f32 v[28:29], v[28:29], v[10:11] op_sel_hi:[1,0]
	v_pk_mul_f32 v[26:27], v[26:27], v[10:11] op_sel_hi:[1,0]
	v_pk_mul_f32 v[24:25], v[24:25], v[10:11] op_sel_hi:[1,0]
	v_pk_mul_f32 v[22:23], v[22:23], v[10:11] op_sel_hi:[1,0]
	v_pk_mul_f32 v[20:21], v[20:21], v[10:11] op_sel_hi:[1,0]
	v_pk_mul_f32 v[18:19], v[18:19], v[10:11] op_sel_hi:[1,0]
	v_pk_mul_f32 v[16:17], v[16:17], v[10:11] op_sel_hi:[1,0]
	s_waitcnt lgkmcnt(0)
	v_mfma_f32_32x32x16_bf16 v[32:47], v[164:167], v[2:5], v[32:47]
	v_sub_f32_e32 v13, v58, v0
	v_sub_f32_e32 v14, v59, v0
	v_sub_f32_e32 v15, v60, v0
	v_sub_f32_e32 v48, v61, v0
	v_sub_f32_e32 v51, v62, v0
	v_exp_f32_e32 v13, v13
	v_exp_f32_e32 v14, v14
	v_mfma_f32_32x32x16_bf16 v[16:31], v[168:171], v[2:5], v[16:31]
	v_sub_f32_e32 v3, v63, v0
	v_exp_f32_e32 v15, v15
	v_exp_f32_e32 v48, v48
	v_exp_f32_e32 v2, v51
	v_exp_f32_e32 v3, v3
	v_cvt_pk_bf16_f32 v6, v11, v12
	v_cvt_pk_bf16_f32 v7, v13, v14
	v_cvt_pk_bf16_f32 v8, v15, v48
	v_cvt_pk_bf16_f32 v9, v2, v3
	v_add_f32_e32 v4, v13, v50
	v_add_f32_e32 v4, v14, v4
	v_mfma_f32_32x32x16_bf16 v[32:47], v[64:67], v[6:9], v[32:47]
	v_add_f32_e32 v4, v15, v4
	v_add_f32_e32 v4, v48, v4
	v_add_f32_e32 v2, v2, v4
	v_add_f32_e32 v4, v3, v2
	v_fmac_f32_e32 v4, v98, v10
	v_mfma_f32_32x32x16_bf16 v[16:31], v[172:175], v[6:9], v[16:31]
	s_cbranch_vccnz .LBB0_381
	s_nop 4
	ds_write2st64_b32 v123, v32, v33 offset0:192 offset1:193
	s_nop 4
	ds_write2st64_b32 v123, v16, v17 offset0:208 offset1:209
	ds_write2st64_b32 v123, v34, v35 offset0:194 offset1:195
	ds_write2st64_b32 v123, v18, v19 offset0:210 offset1:211
	ds_write2st64_b32 v123, v36, v37 offset0:196 offset1:197
	ds_write2st64_b32 v123, v20, v21 offset0:212 offset1:213
	ds_write2st64_b32 v123, v38, v39 offset0:198 offset1:199
	ds_write2st64_b32 v123, v22, v23 offset0:214 offset1:215
	ds_write2st64_b32 v123, v40, v41 offset0:200 offset1:201
	ds_write2st64_b32 v123, v24, v25 offset0:216 offset1:217
	ds_write2st64_b32 v123, v42, v43 offset0:202 offset1:203
	ds_write2st64_b32 v123, v26, v27 offset0:218 offset1:219
	ds_write2st64_b32 v123, v44, v45 offset0:204 offset1:205
	ds_write2st64_b32 v123, v28, v29 offset0:220 offset1:221
	ds_write2st64_b32 v123, v46, v47 offset0:206 offset1:207
	ds_write2st64_b32 v123, v30, v31 offset0:222 offset1:223
	ds_write2st64_b32 v123, v0, v4 offset0:224 offset1:225

.LBB0_391:
	s_or_b64 exec, exec, s[2:3]
	s_bitcmp1_b32 s7, 0
	s_cselect_b32 s3, 0, 0x2e00
	s_cselect_b32 s2, 0x2e00, 0
	s_add_i32 s3, s18, s3
	v_add3_u32 v0, s3, v153, v154
	global_load_dwordx4 v[92:95], v[126:127], off
	ds_read_b128 v[128:131], v0
	ds_read_b128 v[132:135], v0 offset:32
	ds_read_b128 v[136:139], v0 offset:64
	ds_read_b128 v[160:163], v0 offset:96
	ds_read_b128 v[164:167], v0 offset:128
	ds_read_b128 v[168:171], v0 offset:160
	v_add3_u32 v0, s3, v102, v155
	v_add_u32_e32 v2, 0x1800, v0
	v_add_u32_e32 v0, 0x2000, v0
	ds_read2_b64 v[172:175], v2 offset0:64 offset1:66
	ds_read2_b64 v[176:179], v2 offset0:68 offset1:70
	ds_read2_b64 v[180:183], v0 offset0:128 offset1:130
	ds_read2_b64 v[184:187], v0 offset0:132 offset1:134
	s_add_i32 s8, s18, s2
	s_waitcnt lgkmcnt(9)
	v_mfma_f32_32x32x16_bf16 v[48:63], v[128:131], v[68:71], 0
	s_waitcnt lgkmcnt(8)
	v_mfma_f32_32x32x16_bf16 v[48:63], v[132:135], v[72:75], v[48:63]
	s_waitcnt lgkmcnt(7)
	v_mfma_f32_32x32x16_bf16 v[48:63], v[136:139], v[76:79], v[48:63]
	s_waitcnt lgkmcnt(6)
	v_mfma_f32_32x32x16_bf16 v[48:63], v[160:163], v[80:83], v[48:63]
	s_waitcnt lgkmcnt(5)
	v_mfma_f32_32x32x16_bf16 v[48:63], v[164:167], v[84:87], v[48:63]
	s_waitcnt lgkmcnt(4)
	v_mfma_f32_32x32x16_bf16 v[48:63], v[168:171], v[88:91], v[48:63]
	s_nop 11
	v_max_f32_e32 v0, v49, v49
	v_max_f32_e32 v2, v48, v48
	v_max_f32_e32 v0, v2, v0
	v_max3_f32 v0, v0, v50, v51
	v_max3_f32 v0, v0, v52, v53
	v_max3_f32 v0, v0, v54, v55
	v_max3_f32 v0, v0, v56, v57
	v_max3_f32 v0, v0, v58, v59
	v_max3_f32 v0, v0, v60, v61
	v_max3_f32 v0, v0, v62, v63
	v_mov_b32_e32 v2, v0
	s_nop 1
	v_permlane32_swap_b32_e32 v2, v0
	s_nop 1
	v_max3_f32 v119, v121, v0, v2
	v_sub_f32_e32 v0, v121, v119
	v_sub_f32_e32 v2, v48, v119
	v_sub_f32_e32 v3, v49, v119
	v_sub_f32_e32 v4, v50, v119
	v_sub_f32_e32 v5, v51, v119
	v_sub_f32_e32 v6, v52, v119
	v_sub_f32_e32 v7, v53, v119
	v_sub_f32_e32 v8, v54, v119
	v_sub_f32_e32 v9, v55, v119
	v_exp_f32_e32 v2, v2
	v_exp_f32_e32 v3, v3
	v_exp_f32_e32 v4, v4
	v_exp_f32_e32 v5, v5
	v_exp_f32_e32 v6, v6
	v_exp_f32_e32 v7, v7
	v_exp_f32_e32 v8, v8
	v_exp_f32_e32 v9, v9
	v_exp_f32_e32 v0, v0
	v_cvt_pk_bf16_f32 v48, v2, v3
	v_cvt_pk_bf16_f32 v49, v4, v5
	v_cvt_pk_bf16_f32 v50, v6, v7
	v_pk_mul_f32 v[46:47], v[46:47], v[0:1] op_sel_hi:[1,0]
	v_pk_mul_f32 v[44:45], v[44:45], v[0:1] op_sel_hi:[1,0]
	v_pk_mul_f32 v[42:43], v[42:43], v[0:1] op_sel_hi:[1,0]
	v_pk_mul_f32 v[40:41], v[40:41], v[0:1] op_sel_hi:[1,0]
	v_pk_mul_f32 v[38:39], v[38:39], v[0:1] op_sel_hi:[1,0]
	v_pk_mul_f32 v[36:37], v[36:37], v[0:1] op_sel_hi:[1,0]
	v_pk_mul_f32 v[34:35], v[34:35], v[0:1] op_sel_hi:[1,0]
	v_pk_mul_f32 v[32:33], v[32:33], v[0:1] op_sel_hi:[1,0]
	v_pk_mul_f32 v[30:31], v[30:31], v[0:1] op_sel_hi:[1,0]
	v_cvt_pk_bf16_f32 v51, v8, v9
	v_pk_mul_f32 v[28:29], v[28:29], v[0:1] op_sel_hi:[1,0]
	v_pk_mul_f32 v[26:27], v[26:27], v[0:1] op_sel_hi:[1,0]
	v_pk_mul_f32 v[24:25], v[24:25], v[0:1] op_sel_hi:[1,0]
	v_pk_mul_f32 v[22:23], v[22:23], v[0:1] op_sel_hi:[1,0]
	v_pk_mul_f32 v[20:21], v[20:21], v[0:1] op_sel_hi:[1,0]
	v_pk_mul_f32 v[18:19], v[18:19], v[0:1] op_sel_hi:[1,0]
	v_pk_mul_f32 v[16:17], v[16:17], v[0:1] op_sel_hi:[1,0]
	s_waitcnt lgkmcnt(0)
	v_mfma_f32_32x32x16_bf16 v[32:47], v[172:175], v[48:51], v[32:47]
	v_sub_f32_e32 v10, v56, v119
	v_sub_f32_e32 v11, v57, v119
	v_sub_f32_e32 v12, v58, v119
	v_sub_f32_e32 v13, v59, v119
	v_sub_f32_e32 v14, v60, v119
	v_sub_f32_e32 v15, v61, v119
	v_sub_f32_e32 v52, v62, v119
	v_mfma_f32_32x32x16_bf16 v[16:31], v[180:183], v[48:51], v[16:31]
	v_sub_f32_e32 v49, v63, v119
	v_exp_f32_e32 v10, v10
	v_exp_f32_e32 v11, v11
	v_exp_f32_e32 v12, v12
	v_exp_f32_e32 v13, v13
	v_exp_f32_e32 v14, v14
	v_exp_f32_e32 v15, v15
	v_exp_f32_e32 v48, v52
	v_exp_f32_e32 v49, v49
	v_cvt_pk_bf16_f32 v50, v10, v11
	v_cvt_pk_bf16_f32 v51, v12, v13
	v_cvt_pk_bf16_f32 v52, v14, v15
	v_cvt_pk_bf16_f32 v53, v48, v49
	s_nop 1
	v_mfma_f32_32x32x16_bf16 v[32:47], v[176:179], v[50:53], v[32:47]
	v_mfma_f32_32x32x16_bf16 v[16:31], v[184:187], v[50:53], v[16:31]
	v_add3_u32 v50, s8, v148, v149
	s_waitcnt vmcnt(1)
	ds_write_b128 v50, v[96:99]
	s_and_saveexec_b64 s[2:3], s[0:1]
	v_add3_u32 v50, s8, v150, v156
	ds_write_b128 v50, v[64:67]
	s_or_b64 exec, exec, s[2:3]
	v_add_f32_e32 v2, 0, v2
	v_add_f32_e32 v2, v3, v2
	v_add_f32_e32 v2, v4, v2
	v_add_f32_e32 v2, v5, v2
	v_add_f32_e32 v2, v6, v2
	v_add_f32_e32 v2, v7, v2
	v_add_f32_e32 v2, v8, v2
	v_add_f32_e32 v2, v9, v2
	v_add_f32_e32 v2, v10, v2
	v_add_f32_e32 v2, v11, v2
	v_add_f32_e32 v2, v12, v2
	v_add_f32_e32 v2, v13, v2
	v_add_f32_e32 v2, v14, v2
	v_add_f32_e32 v2, v15, v2
	v_add_f32_e32 v2, v48, v2
	v_add_f32_e32 v96, v49, v2
	s_add_i32 s7, s7, 1
	v_fmac_f32_e32 v96, v117, v0
	v_add3_u32 v0, s8, v151, v152
	v_add_u32_e32 v113, 32, v113
	v_lshl_add_u64 v[126:127], v[126:127], 0, 64
	s_cmp_eq_u32 s7, 8
	v_add_u32_e32 v115, 32, v115
	s_waitcnt vmcnt(0)
	ds_write_b128 v0, v[92:95] offset:6656
	s_waitcnt lgkmcnt(0)
	s_barrier
	s_cbranch_scc0 .LBB0_389
	v_add3_u32 v0, s8, v153, v154
	ds_read_b128 v[122:125], v0
	ds_read_b128 v[126:129], v0 offset:32
	ds_read_b128 v[130:133], v0 offset:64
	ds_read_b128 v[134:137], v0 offset:96
	ds_read_b128 v[138:141], v0 offset:128
	ds_read_b128 v[160:163], v0 offset:160
	v_add3_u32 v0, s8, v102, v155
	v_add_u32_e32 v2, 0x1800, v0
	v_add_u32_e32 v0, 0x2000, v0
	v_mov_b32_e32 v14, v1
	v_mov_b32_e32 v15, v1
	ds_read2_b64 v[164:167], v2 offset0:64 offset1:66
	ds_read2_b64 v[64:67], v2 offset0:68 offset1:70
	ds_read2_b64 v[168:171], v0 offset0:128 offset1:130
	ds_read2_b64 v[92:95], v0 offset0:132 offset1:134
	v_mov_b32_e32 v0, v1
	v_mov_b32_e32 v2, v1
	v_mov_b32_e32 v3, v1
	v_mov_b32_e32 v4, v1
	v_mov_b32_e32 v5, v1
	v_mov_b32_e32 v6, v1
	v_mov_b32_e32 v7, v1
	v_mov_b32_e32 v8, v1
	v_mov_b32_e32 v9, v1
	v_mov_b32_e32 v10, v1
	v_mov_b32_e32 v11, v1
	v_mov_b32_e32 v12, v1
	v_mov_b32_e32 v13, v1
	v_mov_b64_e32 v[62:63], v[14:15]
	v_mov_b64_e32 v[60:61], v[12:13]
	v_mov_b64_e32 v[58:59], v[10:11]
	v_mov_b64_e32 v[56:57], v[8:9]
	v_mov_b64_e32 v[54:55], v[6:7]
	v_mov_b64_e32 v[52:53], v[4:5]
	v_mov_b64_e32 v[50:51], v[2:3]
	v_mov_b64_e32 v[48:49], v[0:1]
	s_ashr_i32 s7, s6, 31
	v_mov_b32_e32 v121, v1
	s_waitcnt lgkmcnt(9)
	v_mfma_f32_32x32x16_bf16 v[48:63], v[122:125], v[68:71], v[48:63]
	s_waitcnt lgkmcnt(0)
	s_barrier
	s_add_i32 s5, s5, s26
	v_mfma_f32_32x32x16_bf16 v[48:63], v[126:129], v[72:75], v[48:63]
	v_mfma_f32_32x32x16_bf16 v[48:63], v[130:133], v[76:79], v[48:63]
	v_mfma_f32_32x32x16_bf16 v[48:63], v[134:137], v[80:83], v[48:63]
	v_mfma_f32_32x32x16_bf16 v[48:63], v[138:141], v[84:87], v[48:63]
	v_mfma_f32_32x32x16_bf16 v[48:63], v[160:163], v[88:91], v[48:63]
	s_nop 11
	v_max_f32_e32 v0, v49, v49
	v_max_f32_e32 v2, v48, v48
	v_max_f32_e32 v0, v2, v0
	v_max3_f32 v0, v0, v50, v51
	v_max3_f32 v0, v0, v52, v53
	v_max3_f32 v0, v0, v54, v55
	v_max3_f32 v0, v0, v56, v57
	v_max3_f32 v0, v0, v58, v59
	v_max3_f32 v0, v0, v60, v61
	v_max3_f32 v0, v0, v62, v63
	v_mov_b32_e32 v2, v0
	s_nop 1
	v_permlane32_swap_b32_e32 v2, v0
	s_nop 1
	v_max3_f32 v6, v119, v0, v2
	v_sub_f32_e32 v2, v48, v6
	v_sub_f32_e32 v3, v49, v6
	v_exp_f32_e32 v2, v2
	v_sub_f32_e32 v4, v50, v6
	v_exp_f32_e32 v3, v3
	v_sub_f32_e32 v5, v51, v6
	v_exp_f32_e32 v4, v4
	v_sub_f32_e32 v7, v52, v6
	v_exp_f32_e32 v5, v5
	v_sub_f32_e32 v8, v53, v6
	v_exp_f32_e32 v7, v7
	v_add_f32_e32 v49, 0, v2
	v_sub_f32_e32 v9, v54, v6
	v_exp_f32_e32 v8, v8
	v_add_f32_e32 v49, v3, v49
	v_sub_f32_e32 v10, v55, v6
	v_exp_f32_e32 v9, v9
	v_add_f32_e32 v49, v4, v49
	v_sub_f32_e32 v0, v119, v6
	v_sub_f32_e32 v11, v56, v6
	v_exp_f32_e32 v10, v10
	v_add_f32_e32 v49, v5, v49
	v_sub_f32_e32 v12, v57, v6
	v_exp_f32_e32 v11, v11
	v_add_f32_e32 v49, v7, v49
	v_exp_f32_e32 v0, v0
	v_sub_f32_e32 v13, v58, v6
	v_exp_f32_e32 v12, v12
	v_add_f32_e32 v49, v8, v49
	v_sub_f32_e32 v14, v59, v6
	v_exp_f32_e32 v13, v13
	v_add_f32_e32 v49, v9, v49
	v_sub_f32_e32 v15, v60, v6
	v_exp_f32_e32 v14, v14
	v_add_f32_e32 v49, v10, v49
	v_sub_f32_e32 v48, v61, v6
	v_exp_f32_e32 v15, v15
	v_add_f32_e32 v49, v11, v49
	v_pk_mul_f32 v[46:47], v[46:47], v[0:1] op_sel_hi:[1,0]
	v_pk_mul_f32 v[44:45], v[44:45], v[0:1] op_sel_hi:[1,0]
	v_pk_mul_f32 v[42:43], v[42:43], v[0:1] op_sel_hi:[1,0]
	v_pk_mul_f32 v[40:41], v[40:41], v[0:1] op_sel_hi:[1,0]
	v_pk_mul_f32 v[38:39], v[38:39], v[0:1] op_sel_hi:[1,0]
	v_pk_mul_f32 v[36:37], v[36:37], v[0:1] op_sel_hi:[1,0]
	v_pk_mul_f32 v[34:35], v[34:35], v[0:1] op_sel_hi:[1,0]
	v_pk_mul_f32 v[32:33], v[32:33], v[0:1] op_sel_hi:[1,0]
	v_pk_mul_f32 v[30:31], v[30:31], v[0:1] op_sel_hi:[1,0]
	v_cvt_pk_bf16_f32 v2, v2, v3
	v_cvt_pk_bf16_f32 v3, v4, v5
	v_cvt_pk_bf16_f32 v4, v7, v8
	v_cvt_pk_bf16_f32 v5, v9, v10
	v_pk_mul_f32 v[28:29], v[28:29], v[0:1] op_sel_hi:[1,0]
	v_pk_mul_f32 v[26:27], v[26:27], v[0:1] op_sel_hi:[1,0]
	v_pk_mul_f32 v[24:25], v[24:25], v[0:1] op_sel_hi:[1,0]
	v_pk_mul_f32 v[22:23], v[22:23], v[0:1] op_sel_hi:[1,0]
	v_pk_mul_f32 v[20:21], v[20:21], v[0:1] op_sel_hi:[1,0]
	v_pk_mul_f32 v[18:19], v[18:19], v[0:1] op_sel_hi:[1,0]
	v_pk_mul_f32 v[16:17], v[16:17], v[0:1] op_sel_hi:[1,0]
	v_exp_f32_e32 v48, v48
	v_add_f32_e32 v49, v12, v49
	v_sub_f32_e32 v50, v62, v6
	s_waitcnt lgkmcnt(0)
	v_mfma_f32_32x32x16_bf16 v[32:47], v[164:167], v[2:5], v[32:47]
	v_add_f32_e32 v49, v13, v49
	v_exp_f32_e32 v7, v50
	v_add_f32_e32 v49, v14, v49
	v_add_f32_e32 v49, v15, v49
	v_add_f32_e32 v49, v48, v49
	v_mfma_f32_32x32x16_bf16 v[16:31], v[168:171], v[2:5], v[16:31]
	v_sub_f32_e32 v2, v63, v6
	v_exp_f32_e32 v6, v2
	v_cvt_pk_bf16_f32 v2, v11, v12
	v_cvt_pk_bf16_f32 v3, v13, v14
	v_cvt_pk_bf16_f32 v4, v15, v48
	v_cvt_pk_bf16_f32 v5, v7, v6
	v_add_f32_e32 v7, v7, v49
	v_add_f32_e32 v6, v6, v7
	v_fmac_f32_e32 v6, v96, v0
	ds_bpermute_b32 v0, v103, v6
	v_mfma_f32_32x32x16_bf16 v[32:47], v[64:67], v[2:5], v[32:47]
	s_waitcnt lgkmcnt(0)
	v_add_f32_e32 v0, v6, v0
	v_mfma_f32_32x32x16_bf16 v[16:31], v[92:95], v[2:5], v[16:31]
	v_div_scale_f32 v2, s[2:3], v0, v0, 1.0
	v_rcp_f32_e32 v3, v2
	v_readlane_b32 s2, v253, 6
	v_readlane_b32 s3, v253, 7
	v_fma_f32 v4, -v2, v3, 1.0
	v_fmac_f32_e32 v3, v4, v3
	v_div_scale_f32 v4, vcc, 1.0, v0, 1.0
	v_mul_f32_e32 v5, v4, v3
	v_fma_f32 v6, -v2, v5, v4
	v_fmac_f32_e32 v5, v6, v3
	v_fma_f32 v2, -v2, v5, v4
	v_div_fmas_f32 v2, v2, v3, v5
	v_div_fixup_f32 v0, v2, v0, 1.0
	v_lshl_add_u64 v[2:3], s[6:7], 0, v[108:109]
	v_lshlrev_b64 v[2:3], 10, v[2:3]
	v_lshl_add_u64 v[2:3], s[2:3], 0, v[2:3]
	s_lshl_b32 s2, s12, 1
	s_mov_b32 s3, s4
	v_lshl_add_u64 v[2:3], v[2:3], 0, s[2:3]
	v_pk_mul_f32 v[4:5], v[32:33], v[0:1] op_sel_hi:[1,0]
	v_pk_mul_f32 v[6:7], v[34:35], v[0:1] op_sel_hi:[1,0]
	v_lshl_add_u64 v[2:3], v[2:3], 0, v[120:121]
	v_cvt_pk_bf16_f32 v4, v4, v5
	v_cvt_pk_bf16_f32 v5, v6, v7
	global_store_dwordx2 v[2:3], v[4:5], off
	v_pk_mul_f32 v[4:5], v[16:17], v[0:1] op_sel_hi:[1,0]
	v_pk_mul_f32 v[6:7], v[18:19], v[0:1] op_sel_hi:[1,0]
	v_cvt_pk_bf16_f32 v4, v4, v5
	v_cvt_pk_bf16_f32 v5, v6, v7
	global_store_dwordx2 v[2:3], v[4:5], off offset:64
	v_pk_mul_f32 v[4:5], v[36:37], v[0:1] op_sel_hi:[1,0]
	v_pk_mul_f32 v[6:7], v[38:39], v[0:1] op_sel_hi:[1,0]
	v_cvt_pk_bf16_f32 v4, v4, v5
	v_cvt_pk_bf16_f32 v5, v6, v7
	global_store_dwordx2 v[2:3], v[4:5], off offset:16
	v_pk_mul_f32 v[4:5], v[20:21], v[0:1] op_sel_hi:[1,0]
	v_pk_mul_f32 v[6:7], v[22:23], v[0:1] op_sel_hi:[1,0]
	v_cvt_pk_bf16_f32 v4, v4, v5
	v_cvt_pk_bf16_f32 v5, v6, v7
	global_store_dwordx2 v[2:3], v[4:5], off offset:80
	v_pk_mul_f32 v[4:5], v[40:41], v[0:1] op_sel_hi:[1,0]
	v_pk_mul_f32 v[6:7], v[42:43], v[0:1] op_sel_hi:[1,0]
	v_cvt_pk_bf16_f32 v4, v4, v5
	v_cvt_pk_bf16_f32 v5, v6, v7
	global_store_dwordx2 v[2:3], v[4:5], off offset:32
	v_pk_mul_f32 v[4:5], v[24:25], v[0:1] op_sel_hi:[1,0]
	v_pk_mul_f32 v[6:7], v[26:27], v[0:1] op_sel_hi:[1,0]
	v_cvt_pk_bf16_f32 v4, v4, v5
	v_cvt_pk_bf16_f32 v5, v6, v7
	global_store_dwordx2 v[2:3], v[4:5], off offset:96
	v_pk_mul_f32 v[4:5], v[44:45], v[0:1] op_sel_hi:[1,0]
	v_pk_mul_f32 v[6:7], v[46:47], v[0:1] op_sel_hi:[1,0]
	v_cvt_pk_bf16_f32 v4, v4, v5
	v_cvt_pk_bf16_f32 v5, v6, v7
	global_store_dwordx2 v[2:3], v[4:5], off offset:48
	v_pk_mul_f32 v[4:5], v[28:29], v[0:1] op_sel_hi:[1,0]
	v_pk_mul_f32 v[6:7], v[30:31], v[0:1] op_sel_hi:[1,0]
	v_cvt_pk_bf16_f32 v4, v4, v5
	v_cvt_pk_bf16_f32 v5, v6, v7
	s_cmpk_gt_i32 s5, 0xff
	global_store_dwordx2 v[2:3], v[4:5], off offset:112
	s_cbranch_scc0 .LBB0_384
